# no entry grid.sync + 64B-aligned heads of GEMM K-loops / unit loop / attention steady loop
# baseline (speedup 1.0000x reference)
; #define PG8_BAR __builtin_amdgcn_s_barrier()
; template <class Epi, class Sched, bool ALIGN_EPI = false, bool SP2 = false>
; __device__ __forceinline__ void gemm_phase(PG8_LAS unsigned char* lds, const Gemm g, const Sched& S, const Epi& E) {
;     ...
;         cur = nxt; cA = nA; cB = nB; ++ui;
;         if constexpr (ALIGN_EPI) { if (wr == 1) PG8_BAR; }
;     }
.LBB0_35:
	s_andn2_b64 vcc, exec, s[60:61]
	s_mov_b32 s6, s93
	s_mov_b32 s60, s13
	s_mov_b64 s[62:63], s[40:41]
	s_mov_b64 s[64:65], s[54:55]
	s_cbranch_vccz .LBB0_28
	.p2align	6

; template <class Epi, class Sched, bool ALIGN_EPI = false, bool SP2 = false>
; __device__ __forceinline__ void gemm_phase(PG8_LAS unsigned char* lds, const Gemm g, const Sched& S, const Epi& E) {
;     ...
; #pragma unroll
;         for (int a = 0; a < 2; ++a)
; #pragma unroll
;             for (int b = 0; b < 2; ++b)
; #pragma unroll
;                 for (int m = 0; m < 4; ++m)
; #pragma unroll
;                     for (int n = 0; n < 2; ++n) acc[a][b][m][n] = ini[b][n];
;         cur = nxt; cA = nA; cB = nB; ++ui;
.LBB0_78:
	s_add_u32 s62, s62, 0x80
	s_addc_u32 s63, s63, 0
	s_add_u32 s0, s64, 0x100
	s_waitcnt vmcnt(0)
	v_mov_b64_e32 v[10:11], v[2:3]
	v_mov_b64_e32 v[14:15], v[6:7]
	v_mov_b64_e32 v[18:19], v[2:3]
	v_mov_b64_e32 v[22:23], v[6:7]
	v_mov_b64_e32 v[26:27], v[2:3]
	v_mov_b64_e32 v[30:31], v[6:7]
	v_mov_b64_e32 v[74:75], v[62:63]
	v_mov_b64_e32 v[78:79], v[70:71]
	v_mov_b64_e32 v[82:83], v[62:63]
	v_mov_b64_e32 v[86:87], v[70:71]
	v_mov_b64_e32 v[90:91], v[62:63]
	v_mov_b64_e32 v[94:95], v[70:71]
	v_mov_b64_e32 v[34:35], v[2:3]
	v_mov_b64_e32 v[38:39], v[6:7]
	v_mov_b64_e32 v[42:43], v[2:3]
	v_mov_b64_e32 v[46:47], v[6:7]
	v_mov_b64_e32 v[50:51], v[2:3]
	v_mov_b64_e32 v[54:55], v[6:7]
	v_mov_b64_e32 v[58:59], v[2:3]
	v_mov_b64_e32 v[66:67], v[6:7]
	v_mov_b64_e32 v[100:101], v[62:63]
	v_mov_b64_e32 v[104:105], v[70:71]
	v_mov_b64_e32 v[116:117], v[62:63]
	v_mov_b64_e32 v[120:121], v[70:71]
	v_mov_b64_e32 v[132:133], v[62:63]
	v_mov_b64_e32 v[136:137], v[70:71]
	v_mov_b64_e32 v[148:149], v[62:63]
	v_mov_b64_e32 v[160:161], v[70:71]
	s_addc_u32 s6, s65, 0
	s_mov_b32 s16, 0
	v_mov_b64_e32 v[8:9], v[0:1]
	v_mov_b64_e32 v[12:13], v[4:5]
	v_mov_b64_e32 v[16:17], v[0:1]
	v_mov_b64_e32 v[20:21], v[4:5]
	v_mov_b64_e32 v[24:25], v[0:1]
	v_mov_b64_e32 v[28:29], v[4:5]
	v_mov_b64_e32 v[72:73], v[60:61]
	v_mov_b64_e32 v[76:77], v[68:69]
	v_mov_b64_e32 v[80:81], v[60:61]
	v_mov_b64_e32 v[84:85], v[68:69]
	v_mov_b64_e32 v[88:89], v[60:61]
	v_mov_b64_e32 v[92:93], v[68:69]
	v_mov_b64_e32 v[32:33], v[0:1]
	v_mov_b64_e32 v[36:37], v[4:5]
	v_mov_b64_e32 v[40:41], v[0:1]
	v_mov_b64_e32 v[44:45], v[4:5]
	v_mov_b64_e32 v[48:49], v[0:1]
	v_mov_b64_e32 v[52:53], v[4:5]
	v_mov_b64_e32 v[56:57], v[0:1]
	v_mov_b64_e32 v[64:65], v[4:5]
	v_mov_b64_e32 v[98:99], v[60:61]
	v_mov_b64_e32 v[102:103], v[68:69]
	v_mov_b64_e32 v[114:115], v[60:61]
	v_mov_b64_e32 v[118:119], v[68:69]
	v_mov_b64_e32 v[130:131], v[60:61]
	v_mov_b64_e32 v[134:135], v[68:69]
	v_mov_b64_e32 v[146:147], v[60:61]
	v_mov_b64_e32 v[158:159], v[68:69]
	.p2align	6

; #define DMA_K(t, slot) glds16(ksrc + (long)(t) * KVBLK * PITCH, (unsigned)__builtin_amdgcn_readfirstlane(kdst + (slot)))
; #define DMA_V(t, slot) glds16(vsrc + (long)(t) * KVBLK * PITCH, (unsigned)__builtin_amdgcn_readfirstlane(vdst + (slot)))
; #define WAIT_BAR(N) asm volatile("s_waitcnt vmcnt(" #N ") lgkmcnt(0)\n\ts_barrier":::"memory")
;   #define DMA_K(t,slot) glds16(ksrc+(long)(t)*KVBLK*PITCH,(unsigned)__builtin_amdgcn_readfirstlane(kdst+(slot)))
;   #define DMA_V(t,slot) glds16(vsrc+(long)(t)*KVBLK*PITCH,(unsigned)__builtin_amdgcn_readfirstlane(vdst+(slot)))
;   #define CINIT(X0,X1,tt) do{ const float*fk_=Fl+(tt)*64+4*hi; _Pragma("unroll") for(int g_=0;g_<4;++g_){ const f32x4v a_=*(const f32x4v*)(fk_+8*g_), b_=*(const f32x4v*)(fk_+32+8*g_); \
;       _Pragma("unroll") for(int i_=0;i_<4;++i_){ X0[4*g_+i_]=nb-a_[i_]; X1[4*g_+i_]=nb-b_[i_]; } } }while(0)
;   #define CMASK(P0,P1,t) do{int jb_=(t)-(NT-4); if(jb_>=0)cmask(P0,P1,jb_,qrel,hi);}while(0)
;   #define START(P0,P1) do{ const float rm=rowmax(P0,P1); resc=false; \
;     { const float dl=max2f(rm,0.f);     \
;       mhat=fadd_s(mhat,dl); \
;       _Pragma("unroll") for(int r=0;r<16;++r){P0[r]=fsub_s(P0[r],dl);P1[r]=fsub_s(P1[r],dl);} \
;       nb=fsub_s(nb,dl); } \
;     _Pragma("unroll") for(int r=0;r<16;++r)P0[r]=__builtin_amdgcn_exp2f(P0[r]); }while(0)
;   #define ROT() do{sl_prev=sl_cur;sl_cur=sl_next;sl_next=(sl_next==(NSLOT-1)*SLOTB)?0:sl_next+SLOTB;}while(0)
;   #define CMASK(P0,P1,t) do{}while(0)
;   #define CMASK(P0,P1,t) do{int jb_=(t)-(NT-4); if(jb_>=0)cmask(P0,P1,jb_,qrel,hi);}while(0)
; template<int THRL> __device__ __forceinline__ void attn_unit(int b,int h,int qb,const bf16*Q,const bf16*__restrict__ K,const bf16*__restrict__ V,const unsigned short*GB,unsigned short*Y,const float*Fcum,int ts,char*shm){
;     ...
;   f32x16 pA0,pA1,pB0,pB1;
;   int sl_prev=0,sl_cur=0,sl_next=SLOTB;
;     ...
;   DMA_K(2,2*SLOTB);
;   WAIT_BAR(3);
;   CINIT(pA0,pA1,0);
;   qkt(pA0,pA1,Kbase,qr,r32,hi);asm volatile("s_nop 15\n\ts_nop 7":"+v"(pA0),"+v"(pA1));CMASK(pA0,pA1,0);
;   START(pA0,pA1);
;   _Pragma("unroll") for(int r=0;r<16;++r)pA1[r]=__builtin_amdgcn_exp2f(pA1[r]);
;   CINIT(pB0,pB1,1);
;   WAIT_BAR(0);
;   DMA_K(3,0);DMA_V(1,SLOTB);
;   ROT();
;   kload8(kf,kp0+sl_cur);
;   WAIT_BAR(2);
.LBB0_215:
	v_lshlrev_b32_e32 v34, 1, v32
	v_lshrrev_b32_e32 v32, 2, v32
	v_and_or_b32 v32, v32, 3, v232
	v_lshlrev_b32_e32 v234, 6, v32
	v_max3_f32 v32, v0, v1, v16
	v_and_b32_e32 v235, 32, v34
	v_max3_f32 v34, v2, v3, v17
	v_max3_f32 v32, v32, v18, v19
	s_and_b32 s6, s6, 0x3fffffc0
	v_max3_f32 v32, v32, v4, v5
	v_max3_f32 v34, v34, v6, v7
	s_lshl_b32 s21, s6, 2
	v_max3_f32 v32, v32, v20, v21
	v_max3_f32 v34, v34, v22, v23
	s_add_i32 s36, s16, 0x2000
	v_max3_f32 v32, v32, v8, v9
	v_max3_f32 v34, v34, v10, v11
	s_mov_b32 s34, 1
	v_max3_f32 v32, v32, v24, v25
	v_max3_f32 v34, v34, v26, v27
	v_or3_b32 v240, v235, v233, v234
	v_max3_f32 v32, v32, v12, v13
	v_max3_f32 v34, v34, v14, v15
	s_mov_b32 s31, 0
	v_max3_f32 v32, v32, v28, v29
	v_max3_f32 v34, v34, v30, v31
	s_cmp_lt_i32 s12, 7
	v_max_f32_e32 v32, v32, v34
	v_lshl_add_u32 v238, v230, 2, s21
	v_mov_b32_e32 v34, v32
	s_nop 1
	v_permlane32_swap_b32_e32 v32, v34
	v_max_f32_e32 v32, v32, v34
	v_lshl_add_u32 v236, v232, 2, s21
	v_max_f32_e32 v32, v32, v97
	s_nop 0
	v_sub_f32_e32 v28, v28, v32
	v_sub_f32_e32 v0, v0, v32
	v_sub_f32_e32 v4, v4, v32
	v_sub_f32_e32 v1, v1, v32
	v_sub_f32_e32 v2, v2, v32
	v_sub_f32_e32 v3, v3, v32
	s_nop 0
	v_exp_f32_e32 v76, v28
	v_lshlrev_b32_e32 v28, 2, v232
	v_sub_f32_e32 v5, v5, v32
	v_sub_f32_e32 v6, v6, v32
	v_sub_f32_e32 v7, v7, v32
	v_exp_f32_e32 v80, v0
	v_exp_f32_e32 v84, v4
	v_or_b32_e32 v0, 0x14900, v28
	v_or_b32_e32 v4, 0x14980, v28
	v_exp_f32_e32 v81, v1
	v_exp_f32_e32 v82, v2
	v_exp_f32_e32 v83, v3
	v_exp_f32_e32 v85, v5
	v_exp_f32_e32 v86, v6
	v_exp_f32_e32 v87, v7
	ds_read_b128 v[0:3], v0
	ds_read_b128 v[4:7], v4
	v_sub_f32_e32 v16, v16, v32
	v_sub_f32_e32 v20, v20, v32
	v_sub_f32_e32 v8, v8, v32
	v_sub_f32_e32 v24, v24, v32
	v_sub_f32_e32 v12, v12, v32
	v_sub_f32_e32 v17, v17, v32
	v_sub_f32_e32 v18, v18, v32
	v_sub_f32_e32 v19, v19, v32
	v_sub_f32_e32 v21, v21, v32
	v_sub_f32_e32 v22, v22, v32
	v_sub_f32_e32 v23, v23, v32
	v_sub_f32_e32 v9, v9, v32
	v_sub_f32_e32 v25, v25, v32
	v_sub_f32_e32 v10, v10, v32
	v_sub_f32_e32 v26, v26, v32
	v_sub_f32_e32 v11, v11, v32
	v_sub_f32_e32 v27, v27, v32
	v_sub_f32_e32 v13, v13, v32
	v_sub_f32_e32 v29, v29, v32
	v_sub_f32_e32 v14, v14, v32
	v_sub_f32_e32 v30, v30, v32
	v_sub_f32_e32 v15, v15, v32
	v_sub_f32_e32 v31, v31, v32
	s_nop 0
	v_exp_f32_e32 v88, v8
	v_exp_f32_e32 v92, v12
	v_exp_f32_e32 v64, v16
	v_exp_f32_e32 v68, v20
	v_exp_f32_e32 v72, v24
	v_or_b32_e32 v8, 0x14920, v28
	v_or_b32_e32 v12, 0x149a0, v28
	v_or_b32_e32 v20, 0x14940, v28
	v_or_b32_e32 v24, 0x149c0, v28
	v_or_b32_e32 v16, 0x14960, v28
	v_or_b32_e32 v28, 0x149e0, v28
	v_exp_f32_e32 v89, v9
	v_exp_f32_e32 v90, v10
	v_exp_f32_e32 v91, v11
	v_exp_f32_e32 v93, v13
	v_exp_f32_e32 v94, v14
	v_exp_f32_e32 v95, v15
	v_exp_f32_e32 v65, v17
	v_exp_f32_e32 v66, v18
	v_exp_f32_e32 v67, v19
	v_exp_f32_e32 v69, v21
	v_exp_f32_e32 v70, v22
	v_exp_f32_e32 v71, v23
	v_exp_f32_e32 v73, v25
	v_exp_f32_e32 v74, v26
	v_exp_f32_e32 v75, v27
	v_exp_f32_e32 v77, v29
	v_exp_f32_e32 v78, v30
	v_exp_f32_e32 v79, v31
	ds_read_b128 v[8:11], v8
	ds_read_b128 v[12:15], v12
	ds_read_b128 v[16:19], v16
	ds_read_b128 v[20:23], v20
	ds_read_b128 v[24:27], v24
	ds_read_b128 v[28:31], v28
	s_waitcnt vmcnt(0) lgkmcnt(0)
	s_barrier
	v_sub_f32_e32 v208, v33, v32
	s_waitcnt lgkmcnt(7)
	v_sub_f32_e32 v33, v208, v1
	v_sub_f32_e32 v32, v208, v0
	v_lshl_add_u64 v[0:1], v[204:205], 0, s[14:15]
	s_mov_b32 s6, m0
	s_mov_b32 m0, s0
	s_nop 0
	global_load_lds_dwordx4 v[0:1], off
	s_mov_b32 m0, s6
	v_lshl_add_u64 v[0:1], v[206:207], 0, s[18:19]
	s_mov_b32 s38, m0
	s_mov_b32 m0, s36
	s_nop 0
	global_load_lds_dwordx4 v[0:1], off
	s_mov_b32 m0, s38
	ds_read_b128 v[158:161], v239 offset:8192
	ds_read_b128 v[150:153], v239 offset:8704
	ds_read_b128 v[154:157], v239 offset:10240
	ds_read_b128 v[142:145], v239 offset:10752
	ds_read_b128 v[146:149], v239 offset:12288
	ds_read_b128 v[134:137], v239 offset:12800
	ds_read_b128 v[138:141], v239 offset:14336
	ds_read_b128 v[130:133], v239 offset:14848
	s_waitcnt vmcnt(2) lgkmcnt(0)
	s_barrier
	s_waitcnt lgkmcnt(11)
	v_sub_f32_e32 v47, v208, v19
	v_sub_f32_e32 v46, v208, v18
	v_sub_f32_e32 v45, v208, v17
	v_sub_f32_e32 v44, v208, v16
	s_waitcnt lgkmcnt(10)
	v_sub_f32_e32 v43, v208, v23
	v_sub_f32_e32 v42, v208, v22
	v_sub_f32_e32 v41, v208, v21
	v_sub_f32_e32 v40, v208, v20
	v_sub_f32_e32 v39, v208, v11
	v_sub_f32_e32 v38, v208, v10
	v_sub_f32_e32 v37, v208, v9
	v_sub_f32_e32 v36, v208, v8
	v_sub_f32_e32 v35, v208, v3
	v_sub_f32_e32 v34, v208, v2
	s_waitcnt lgkmcnt(8)
	v_sub_f32_e32 v63, v208, v31
	v_sub_f32_e32 v62, v208, v30
	v_sub_f32_e32 v61, v208, v29
	v_sub_f32_e32 v60, v208, v28
	v_sub_f32_e32 v59, v208, v27
	v_sub_f32_e32 v58, v208, v26
	v_sub_f32_e32 v57, v208, v25
	v_sub_f32_e32 v56, v208, v24
	v_sub_f32_e32 v55, v208, v15
	v_sub_f32_e32 v54, v208, v14
	v_sub_f32_e32 v53, v208, v13
	v_sub_f32_e32 v52, v208, v12
	v_sub_f32_e32 v51, v208, v7
	v_sub_f32_e32 v50, v208, v6
	v_sub_f32_e32 v49, v208, v5
	v_sub_f32_e32 v48, v208, v4
	s_movk_i32 s6, 0x2000
	v_cmp_gt_u32_e64 s[38:39], 32, v229
	s_cbranch_scc1 .LBB0_231
	v_mov_b32_e32 v0, 0x14a00
	v_mov_b32_e32 v16, v97
	v_mov_b32_e32 v17, v97
	v_lshl_or_b32 v186, v231, 4, v0
	s_mov_b64 s[52:53], 0x50000
	v_mov_b32_e32 v18, v97
	v_mov_b32_e32 v19, v97
	v_mov_b32_e32 v20, v97
	v_mov_b32_e32 v21, v97
	v_mov_b32_e32 v22, v97
	v_mov_b32_e32 v23, v97
	v_mov_b32_e32 v24, v97
	v_mov_b32_e32 v25, v97
	v_mov_b32_e32 v26, v97
	v_mov_b32_e32 v27, v97
	v_mov_b32_e32 v28, v97
	v_mov_b32_e32 v29, v97
	v_mov_b32_e32 v30, v97
	v_mov_b32_e32 v31, v97
	v_mov_b64_e32 v[0:1], v[16:17]
	v_lshl_add_u64 v[182:183], v[206:207], 0, s[14:15]
	v_lshl_add_u64 v[184:185], v[204:205], 0, s[52:53]
	s_mov_b32 s41, 0
	s_movk_i32 s31, 0x4000
	s_movk_i32 s36, 0x2000
	v_mov_b32_e32 v241, 0
	s_mov_b32 s34, 6
	v_mov_b64_e32 v[2:3], v[18:19]
	v_mov_b64_e32 v[4:5], v[20:21]
	v_mov_b64_e32 v[6:7], v[22:23]
	v_mov_b64_e32 v[8:9], v[24:25]
	v_mov_b64_e32 v[10:11], v[26:27]
	v_mov_b64_e32 v[12:13], v[28:29]
	v_mov_b64_e32 v[14:15], v[30:31]
	.p2align	6

; template <class Epi, class Sched, bool ALIGN_EPI = false, bool SP2 = false>
; __device__ __forceinline__ void gemm_phase(PG8_LAS unsigned char* lds, const Gemm g, const Sched& S, const Epi& E) {
;     ...
; #pragma unroll
;         for (int a = 0; a < 2; ++a)
; #pragma unroll
;             for (int b = 0; b < 2; ++b)
; #pragma unroll
;                 for (int m = 0; m < 4; ++m)
; #pragma unroll
;                     for (int n = 0; n < 2; ++n) acc[a][b][m][n] = ini[b][n];
;         cur = nxt; cA = nA; cB = nB; ++ui;
.LBB0_398:
	s_add_u32 s60, s60, 0x80
	s_addc_u32 s61, s61, 0
	s_add_u32 s55, s62, 0x100
	s_waitcnt vmcnt(0)
	v_mov_b64_e32 v[18:19], v[2:3]
	v_mov_b64_e32 v[22:23], v[6:7]
	v_mov_b64_e32 v[26:27], v[2:3]
	v_mov_b64_e32 v[30:31], v[6:7]
	v_mov_b64_e32 v[34:35], v[2:3]
	v_mov_b64_e32 v[38:39], v[6:7]
	v_mov_b64_e32 v[74:75], v[10:11]
	v_mov_b64_e32 v[78:79], v[14:15]
	v_mov_b64_e32 v[82:83], v[10:11]
	v_mov_b64_e32 v[86:87], v[14:15]
	v_mov_b64_e32 v[90:91], v[10:11]
	v_mov_b64_e32 v[94:95], v[14:15]
	v_mov_b64_e32 v[42:43], v[2:3]
	v_mov_b64_e32 v[46:47], v[6:7]
	v_mov_b64_e32 v[50:51], v[2:3]
	v_mov_b64_e32 v[54:55], v[6:7]
	v_mov_b64_e32 v[58:59], v[2:3]
	v_mov_b64_e32 v[62:63], v[6:7]
	v_mov_b64_e32 v[66:67], v[2:3]
	v_mov_b64_e32 v[70:71], v[6:7]
	v_mov_b64_e32 v[100:101], v[10:11]
	v_mov_b64_e32 v[104:105], v[14:15]
	v_mov_b64_e32 v[108:109], v[10:11]
	v_mov_b64_e32 v[112:113], v[14:15]
	v_mov_b64_e32 v[116:117], v[10:11]
	v_mov_b64_e32 v[120:121], v[14:15]
	v_mov_b64_e32 v[124:125], v[10:11]
	v_mov_b64_e32 v[128:129], v[14:15]
	s_addc_u32 s73, s63, 0
	s_mov_b32 s62, 0
	v_mov_b64_e32 v[16:17], v[0:1]
	v_mov_b64_e32 v[20:21], v[4:5]
	v_mov_b64_e32 v[24:25], v[0:1]
	v_mov_b64_e32 v[28:29], v[4:5]
	v_mov_b64_e32 v[32:33], v[0:1]
	v_mov_b64_e32 v[36:37], v[4:5]
	v_mov_b64_e32 v[72:73], v[8:9]
	v_mov_b64_e32 v[76:77], v[12:13]
	v_mov_b64_e32 v[80:81], v[8:9]
	v_mov_b64_e32 v[84:85], v[12:13]
	v_mov_b64_e32 v[88:89], v[8:9]
	v_mov_b64_e32 v[92:93], v[12:13]
	v_mov_b64_e32 v[40:41], v[0:1]
	v_mov_b64_e32 v[44:45], v[4:5]
	v_mov_b64_e32 v[48:49], v[0:1]
	v_mov_b64_e32 v[52:53], v[4:5]
	v_mov_b64_e32 v[56:57], v[0:1]
	v_mov_b64_e32 v[60:61], v[4:5]
	v_mov_b64_e32 v[64:65], v[0:1]
	v_mov_b64_e32 v[68:69], v[4:5]
	v_mov_b64_e32 v[98:99], v[8:9]
	v_mov_b64_e32 v[102:103], v[12:13]
	v_mov_b64_e32 v[106:107], v[8:9]
	v_mov_b64_e32 v[110:111], v[12:13]
	v_mov_b64_e32 v[114:115], v[8:9]
	v_mov_b64_e32 v[118:119], v[12:13]
	v_mov_b64_e32 v[122:123], v[8:9]
	v_mov_b64_e32 v[126:127], v[12:13]
	.p2align	6

; template <class Epi, class Sched, bool ALIGN_EPI = false, bool SP2 = false>
; __device__ __forceinline__ void gemm_phase(PG8_LAS unsigned char* lds, const Gemm g, const Sched& S, const Epi& E) {
;     ...
; #pragma unroll
;     for (int b = 0; b < 2; ++b)
; #pragma unroll
;         for (int n = 0; n < 2; ++n) ini[b][n] = (f32x4){0.f, 0.f, 0.f, 0.f};
;     if constexpr (Epi::ACC_INIT) E.acc_init(ini, cur);
; #pragma unroll
;     for (int a = 0; a < 2; ++a)
; #pragma unroll
;         for (int b = 0; b < 2; ++b)
; #pragma unroll
;             for (int m = 0; m < 4; ++m)
; #pragma unroll
;                 for (int n = 0; n < 2; ++n) acc[a][b][m][n] = ini[b][n];
;     ...
; #pragma unroll
;         for (int a = 0; a < 2; ++a)
; #pragma unroll
;             for (int b = 0; b < 2; ++b)
; #pragma unroll
;                 for (int m = 0; m < 4; ++m)
; #pragma unroll
;                     for (int n = 0; n < 2; ++n) acc[a][b][m][n] = ini[b][n];
;         cur = nxt; cA = nA; cB = nB; ++ui;
.LBB0_438:
	v_mov_b32_e32 v3, 0
	s_andn2_b64 vcc, exec, s[60:61]
	v_mov_b32_e32 v2, v3
	v_mov_b32_e32 v1, v3
	v_mov_b32_e32 v0, v3
	v_mov_b32_e32 v7, v3
	v_mov_b32_e32 v6, v3
	v_mov_b32_e32 v5, v3
	v_mov_b32_e32 v4, v3
	v_mov_b32_e32 v19, v3
	v_mov_b32_e32 v18, v3
	v_mov_b32_e32 v17, v3
	v_mov_b32_e32 v16, v3
	v_mov_b32_e32 v23, v3
	v_mov_b32_e32 v22, v3
	v_mov_b32_e32 v21, v3
	v_mov_b32_e32 v20, v3
	v_mov_b32_e32 v129, v3
	v_mov_b32_e32 v128, v3
	v_mov_b32_e32 v127, v3
	v_mov_b32_e32 v126, v3
	v_mov_b32_e32 v125, v3
	v_mov_b32_e32 v124, v3
	v_mov_b32_e32 v123, v3
	v_mov_b32_e32 v122, v3
	v_mov_b32_e32 v113, v3
	v_mov_b32_e32 v112, v3
	v_mov_b32_e32 v111, v3
	v_mov_b32_e32 v110, v3
	v_mov_b32_e32 v109, v3
	v_mov_b32_e32 v108, v3
	v_mov_b32_e32 v107, v3
	v_mov_b32_e32 v106, v3
	v_mov_b32_e32 v95, v3
	v_mov_b32_e32 v94, v3
	v_mov_b32_e32 v93, v3
	v_mov_b32_e32 v92, v3
	v_mov_b32_e32 v91, v3
	v_mov_b32_e32 v90, v3
	v_mov_b32_e32 v89, v3
	v_mov_b32_e32 v88, v3
	v_mov_b32_e32 v79, v3
	v_mov_b32_e32 v78, v3
	v_mov_b32_e32 v77, v3
	v_mov_b32_e32 v76, v3
	v_mov_b32_e32 v75, v3
	v_mov_b32_e32 v74, v3
	v_mov_b32_e32 v73, v3
	v_mov_b32_e32 v72, v3
	v_mov_b32_e32 v121, v3
	v_mov_b32_e32 v120, v3
	v_mov_b32_e32 v119, v3
	v_mov_b32_e32 v118, v3
	v_mov_b32_e32 v117, v3
	v_mov_b32_e32 v116, v3
	v_mov_b32_e32 v115, v3
	v_mov_b32_e32 v114, v3
	v_mov_b32_e32 v105, v3
	v_mov_b32_e32 v104, v3
	v_mov_b32_e32 v103, v3
	v_mov_b32_e32 v102, v3
	v_mov_b32_e32 v101, v3
	v_mov_b32_e32 v100, v3
	v_mov_b32_e32 v99, v3
	v_mov_b32_e32 v98, v3
	v_mov_b32_e32 v87, v3
	v_mov_b32_e32 v86, v3
	v_mov_b32_e32 v85, v3
	v_mov_b32_e32 v84, v3
	v_mov_b32_e32 v83, v3
	v_mov_b32_e32 v82, v3
	v_mov_b32_e32 v81, v3
	v_mov_b32_e32 v80, v3
	v_mov_b32_e32 v71, v3
	v_mov_b32_e32 v70, v3
	v_mov_b32_e32 v69, v3
	v_mov_b32_e32 v68, v3
	v_mov_b32_e32 v67, v3
	v_mov_b32_e32 v66, v3
	v_mov_b32_e32 v65, v3
	v_mov_b32_e32 v64, v3
	v_mov_b32_e32 v63, v3
	v_mov_b32_e32 v62, v3
	v_mov_b32_e32 v61, v3
	v_mov_b32_e32 v60, v3
	v_mov_b32_e32 v59, v3
	v_mov_b32_e32 v58, v3
	v_mov_b32_e32 v57, v3
	v_mov_b32_e32 v56, v3
	v_mov_b32_e32 v47, v3
	v_mov_b32_e32 v46, v3
	v_mov_b32_e32 v45, v3
	v_mov_b32_e32 v44, v3
	v_mov_b32_e32 v43, v3
	v_mov_b32_e32 v42, v3
	v_mov_b32_e32 v41, v3
	v_mov_b32_e32 v40, v3
	v_mov_b32_e32 v35, v3
	v_mov_b32_e32 v34, v3
	v_mov_b32_e32 v33, v3
	v_mov_b32_e32 v32, v3
	v_mov_b32_e32 v27, v3
	v_mov_b32_e32 v26, v3
	v_mov_b32_e32 v25, v3
	v_mov_b32_e32 v24, v3
	v_mov_b32_e32 v15, v3
	v_mov_b32_e32 v14, v3
	v_mov_b32_e32 v13, v3
	v_mov_b32_e32 v12, v3
	v_mov_b32_e32 v11, v3
	v_mov_b32_e32 v10, v3
	v_mov_b32_e32 v9, v3
	v_mov_b32_e32 v8, v3
	v_mov_b32_e32 v55, v3
	v_mov_b32_e32 v54, v3
	v_mov_b32_e32 v53, v3
	v_mov_b32_e32 v52, v3
	v_mov_b32_e32 v51, v3
	v_mov_b32_e32 v50, v3
	v_mov_b32_e32 v49, v3
	v_mov_b32_e32 v48, v3
	v_mov_b32_e32 v39, v3
	v_mov_b32_e32 v38, v3
	v_mov_b32_e32 v37, v3
	v_mov_b32_e32 v36, v3
	v_mov_b32_e32 v31, v3
	v_mov_b32_e32 v30, v3
	v_mov_b32_e32 v29, v3
	v_mov_b32_e32 v28, v3
	s_cbranch_vccnz .LBB0_441
	s_add_u32 s66, s66, 0x80
	s_addc_u32 s67, s67, 0
	s_add_u32 s71, s68, 0x100
	v_mov_b32_e32 v28, 0
	s_addc_u32 s73, s69, 0
	s_mov_b32 s68, 0
	v_mov_b32_e32 v29, v28
	v_mov_b32_e32 v30, v28
	v_mov_b32_e32 v31, v28
	v_mov_b32_e32 v36, v28
	v_mov_b32_e32 v37, v28
	v_mov_b32_e32 v38, v28
	v_mov_b32_e32 v39, v28
	v_mov_b32_e32 v48, v28
	v_mov_b32_e32 v49, v28
	v_mov_b32_e32 v50, v28
	v_mov_b32_e32 v51, v28
	v_mov_b32_e32 v52, v28
	v_mov_b32_e32 v53, v28
	v_mov_b32_e32 v54, v28
	v_mov_b32_e32 v55, v28
	v_mov_b32_e32 v8, v28
	v_mov_b32_e32 v9, v28
	v_mov_b32_e32 v10, v28
	v_mov_b32_e32 v11, v28
	v_mov_b32_e32 v12, v28
	v_mov_b32_e32 v13, v28
	v_mov_b32_e32 v14, v28
	v_mov_b32_e32 v15, v28
	v_mov_b32_e32 v24, v28
	v_mov_b32_e32 v25, v28
	v_mov_b32_e32 v26, v28
	v_mov_b32_e32 v27, v28
	v_mov_b32_e32 v32, v28
	v_mov_b32_e32 v33, v28
	v_mov_b32_e32 v34, v28
	v_mov_b32_e32 v35, v28
	v_mov_b32_e32 v40, v28
	v_mov_b32_e32 v41, v28
	v_mov_b32_e32 v42, v28
	v_mov_b32_e32 v43, v28
	v_mov_b32_e32 v44, v28
	v_mov_b32_e32 v45, v28
	v_mov_b32_e32 v46, v28
	v_mov_b32_e32 v47, v28
	v_mov_b32_e32 v56, v28
	v_mov_b32_e32 v57, v28
	v_mov_b32_e32 v58, v28
	v_mov_b32_e32 v59, v28
	v_mov_b32_e32 v60, v28
	v_mov_b32_e32 v61, v28
	v_mov_b32_e32 v62, v28
	v_mov_b32_e32 v63, v28
	v_mov_b32_e32 v64, v28
	v_mov_b32_e32 v65, v28
	v_mov_b32_e32 v66, v28
	v_mov_b32_e32 v67, v28
	v_mov_b32_e32 v68, v28
	v_mov_b32_e32 v69, v28
	v_mov_b32_e32 v70, v28
	v_mov_b32_e32 v71, v28
	v_mov_b32_e32 v80, v28
	v_mov_b32_e32 v81, v28
	v_mov_b32_e32 v82, v28
	v_mov_b32_e32 v83, v28
	v_mov_b32_e32 v84, v28
	v_mov_b32_e32 v85, v28
	v_mov_b32_e32 v86, v28
	v_mov_b32_e32 v87, v28
	v_mov_b32_e32 v98, v28
	v_mov_b32_e32 v99, v28
	v_mov_b32_e32 v100, v28
	v_mov_b32_e32 v101, v28
	v_mov_b32_e32 v102, v28
	v_mov_b32_e32 v103, v28
	v_mov_b32_e32 v104, v28
	v_mov_b32_e32 v105, v28
	v_mov_b32_e32 v114, v28
	v_mov_b32_e32 v115, v28
	v_mov_b32_e32 v116, v28
	v_mov_b32_e32 v117, v28
	v_mov_b32_e32 v118, v28
	v_mov_b32_e32 v119, v28
	v_mov_b32_e32 v120, v28
	v_mov_b32_e32 v121, v28
	v_mov_b32_e32 v72, v28
	v_mov_b32_e32 v73, v28
	v_mov_b32_e32 v74, v28
	v_mov_b32_e32 v75, v28
	v_mov_b32_e32 v76, v28
	v_mov_b32_e32 v77, v28
	v_mov_b32_e32 v78, v28
	v_mov_b32_e32 v79, v28
	v_mov_b32_e32 v88, v28
	v_mov_b32_e32 v89, v28
	v_mov_b32_e32 v90, v28
	v_mov_b32_e32 v91, v28
	v_mov_b32_e32 v92, v28
	v_mov_b32_e32 v93, v28
	v_mov_b32_e32 v94, v28
	v_mov_b32_e32 v95, v28
	v_mov_b32_e32 v106, v28
	v_mov_b32_e32 v107, v28
	v_mov_b32_e32 v108, v28
	v_mov_b32_e32 v109, v28
	v_mov_b32_e32 v110, v28
	v_mov_b32_e32 v111, v28
	v_mov_b32_e32 v112, v28
	v_mov_b32_e32 v113, v28
	v_mov_b32_e32 v122, v28
	v_mov_b32_e32 v123, v28
	v_mov_b32_e32 v124, v28
	v_mov_b32_e32 v125, v28
	v_mov_b32_e32 v126, v28
	v_mov_b32_e32 v127, v28
	v_mov_b32_e32 v128, v28
	v_mov_b32_e32 v129, v28
	v_mov_b32_e32 v20, v28
	v_mov_b32_e32 v21, v28
	v_mov_b32_e32 v22, v28
	v_mov_b32_e32 v23, v28
	v_mov_b32_e32 v16, v28
	v_mov_b32_e32 v17, v28
	v_mov_b32_e32 v18, v28
	v_mov_b32_e32 v19, v28
	v_mov_b32_e32 v4, v28
	v_mov_b32_e32 v5, v28
	v_mov_b32_e32 v6, v28
	v_mov_b32_e32 v7, v28
	v_mov_b32_e32 v0, v28
	v_mov_b32_e32 v1, v28
	v_mov_b32_e32 v2, v28
	v_mov_b32_e32 v3, v28
	.p2align	6
